# v44 + RWKV slot A: all 8 LDS operand reads issued up front, XF MFMA chain first, Z after XF write
# baseline (speedup 1.0000x reference)
; #define LAS __attribute__((address_space(3)))
; __device__ __forceinline__ f32x4 mfma16(bf16x8 a, bf16x8 b, f32x4 c) { return __builtin_amdgcn_mfma_f32_16x16x32_bf16(a, b, c, 0, 0, 0); }
; __device__ __forceinline__ void rwkv_chunk_item(const P& p, const Ctx& c, int seg, int w, bool save) {
;     ...
;         if (c.wv >= 4) {
;             f32x4 Xt = (f32x4){0.f, 0.f, 0.f, 0.f};
; #pragma unroll
;             for (int kk = 0; kk < 2; ++kk) { const bf16x8 a = *(const LAS bf16x8*)(S0I + (mtq * 16 + l15) * 72 + kk * 32 + quad * 8);
;                 Xt = mfma16(a, *(const LAS bf16x8*)(EA + l15 * 72 + kk * 32 + quad * 8), Xt); Zt = mfma16(a, *(const LAS bf16x8*)(EA + (16 + l15) * 72 + kk * 32 + quad * 8), Zt); }
;             Xt = mfma16(*(const LAS bf16x8*)(UV + (mtq * 16 + l15) * 40 + quad * 8), *(const LAS bf16x8*)(MT1 + l15 * 40 + quad * 8), Xt);
; #pragma unroll
;             for (int jj = 0; jj < 4; ++jj) XF[(mtq * 16 + quad * 4 + jj) * 17 + l15] = Xt[jj];
;         }
.LBB0_888:
	s_and_b32 s87, s86, 1
	s_mul_i32 s2, s87, 0x5c00
	s_add_i32 s88, s2, 0
	v_add_u32_e32 v45, s35, v82
	v_lshlrev_b32_e32 v85, 4, v83
	v_mul_lo_u32 v84, v82, s64
	v_mov_b32_e32 v22, 0
	s_andn2_b64 vcc, exec, s[56:57]
	v_mul_lo_u32 v87, v45, s64
	v_add3_u32 v86, s88, v84, v85
	v_mov_b32_e32 v23, 0
	v_mov_b32_e32 v24, 0
	v_mov_b32_e32 v25, 0
	s_cbranch_vccnz .LBB0_890
	v_mul_lo_u32 v22, v45, s63
	v_add3_u32 v45, 0, v22, v85
	v_mul_lo_u32 v22, v82, s63
	v_add3_u32 v54, s88, v22, v85
	v_add3_u32 v129, s88, v87, v85
	ds_read_b128 v[22:25], v45 offset:47104
	ds_read_b128 v[46:49], v54
	ds_read_b128 v[88:91], v45 offset:47168
	ds_read_b128 v[92:95], v54 offset:64
	ds_read_b128 v[96:99], v129 offset:14336
	ds_read_b128 v[100:103], v86 offset:19456
	ds_read_b128 v[50:53], v54 offset:2304
	ds_read_b128 v[124:127], v54 offset:2368
	s_movk_i32 s2, 0x44
	v_lshl_add_u32 v45, v83, 2, s35
	v_lshlrev_b32_e32 v54, 2, v82
	v_mul_lo_u32 v45, v45, s2
	v_add3_u32 v45, 0, v54, v45
	v_add_u32_e32 v45, 0xdc00, v45
	s_waitcnt lgkmcnt(6)
	v_mfma_f32_16x16x32_bf16 v[46:49], v[22:25], v[46:49], 0
	s_waitcnt lgkmcnt(4)
	v_mfma_f32_16x16x32_bf16 v[46:49], v[88:91], v[92:95], v[46:49]
	s_waitcnt lgkmcnt(2)
	v_mfma_f32_16x16x32_bf16 v[46:49], v[96:99], v[100:103], v[46:49]
	s_nop 7
	s_nop 1
	ds_write2_b32 v45, v46, v47 offset1:17
	ds_write2_b32 v45, v48, v49 offset0:34 offset1:51
	s_waitcnt lgkmcnt(2)
	v_mfma_f32_16x16x32_bf16 v[22:25], v[22:25], v[50:53], 0
	v_mfma_f32_16x16x32_bf16 v[22:25], v[88:91], v[124:127], v[22:25]
